# attention PV: steady 1 MFMA : 2 tr-read interleave, 7-deep fragment ring (same 32 VGPRs) instead of 8-read bursts
# speedup vs baseline: 1.0253x; 1.0139x over previous
.LBB0_517:
	v_cndmask_b32_e64 v231, v234, v231, s[4:5]
	v_mul_f32_e32 v192, 0xbe0293ee, v231
	v_fmamk_f32 v144, v144, 0x3e0293ee, v192
	v_fmamk_f32 v145, v145, 0x3e0293ee, v192
	v_fmamk_f32 v146, v146, 0x3e0293ee, v192
	v_fmamk_f32 v147, v147, 0x3e0293ee, v192
	v_fmamk_f32 v148, v148, 0x3e0293ee, v192
	v_fmamk_f32 v149, v149, 0x3e0293ee, v192
	v_fmamk_f32 v150, v150, 0x3e0293ee, v192
	v_fmamk_f32 v151, v151, 0x3e0293ee, v192
	v_fmamk_f32 v152, v152, 0x3e0293ee, v192
	v_fmamk_f32 v153, v153, 0x3e0293ee, v192
	v_fmamk_f32 v154, v154, 0x3e0293ee, v192
	v_fmamk_f32 v155, v155, 0x3e0293ee, v192
	v_fmamk_f32 v156, v156, 0x3e0293ee, v192
	v_fmamk_f32 v157, v157, 0x3e0293ee, v192
	v_fmamk_f32 v158, v158, 0x3e0293ee, v192
	v_fmamk_f32 v159, v159, 0x3e0293ee, v192
	v_fmamk_f32 v128, v128, 0x3e0293ee, v192
	v_fmamk_f32 v129, v129, 0x3e0293ee, v192
	v_fmamk_f32 v130, v130, 0x3e0293ee, v192
	v_fmamk_f32 v131, v131, 0x3e0293ee, v192
	v_fmamk_f32 v132, v132, 0x3e0293ee, v192
	v_fmamk_f32 v133, v133, 0x3e0293ee, v192
	v_fmamk_f32 v134, v134, 0x3e0293ee, v192
	v_fmamk_f32 v135, v135, 0x3e0293ee, v192
	v_fmamk_f32 v136, v136, 0x3e0293ee, v192
	v_fmamk_f32 v137, v137, 0x3e0293ee, v192
	v_fmamk_f32 v138, v138, 0x3e0293ee, v192
	v_fmamk_f32 v139, v139, 0x3e0293ee, v192
	v_fmamk_f32 v140, v140, 0x3e0293ee, v192
	v_fmamk_f32 v141, v141, 0x3e0293ee, v192
	v_fmamk_f32 v142, v142, 0x3e0293ee, v192
	v_fmac_f32_e32 v192, 0x3e0293ee, v143
	v_exp_f32_e32 v143, v144
	v_exp_f32_e32 v145, v145
	v_exp_f32_e32 v146, v146
	v_exp_f32_e32 v147, v147
	v_exp_f32_e32 v148, v148
	v_exp_f32_e32 v193, v128
	v_exp_f32_e32 v149, v149
	v_add_f32_e32 v128, v145, v143
	v_exp_f32_e32 v150, v150
	v_add_f32_e32 v128, v146, v128
	v_exp_f32_e32 v151, v151
	v_add_f32_e32 v128, v147, v128
	v_exp_f32_e32 v152, v152
	v_add_f32_e32 v128, v148, v128
	v_exp_f32_e32 v153, v153
	v_add_f32_e32 v128, v149, v128
	v_exp_f32_e32 v154, v154
	v_add_f32_e32 v128, v150, v128
	v_exp_f32_e32 v155, v155
	v_add_f32_e32 v128, v151, v128
	v_exp_f32_e32 v156, v156
	v_add_f32_e32 v128, v152, v128
	v_exp_f32_e32 v157, v157
	v_add_f32_e32 v128, v153, v128
	v_exp_f32_e32 v158, v158
	v_add_f32_e32 v128, v154, v128
	v_exp_f32_e32 v159, v159
	v_add_f32_e32 v128, v155, v128
	v_add_f32_e32 v128, v156, v128
	v_exp_f32_e32 v194, v129
	v_add_f32_e32 v128, v157, v128
	v_exp_f32_e32 v195, v130
	v_add_f32_e32 v128, v158, v128
	v_exp_f32_e32 v196, v131
	v_add_f32_e32 v128, v159, v128
	v_exp_f32_e32 v197, v132
	v_add_f32_e32 v128, v193, v128
	v_exp_f32_e32 v198, v133
	v_add_f32_e32 v128, v194, v128
	v_exp_f32_e32 v199, v134
	v_add_f32_e32 v128, v195, v128
	v_exp_f32_e32 v135, v135
	v_add_f32_e32 v128, v196, v128
	v_exp_f32_e32 v200, v136
	v_add_f32_e32 v128, v197, v128
	v_exp_f32_e32 v201, v137
	v_add_f32_e32 v128, v198, v128
	v_exp_f32_e32 v202, v138
	v_add_f32_e32 v128, v199, v128
	v_exp_f32_e32 v203, v139
	v_add_f32_e32 v128, v135, v128
	v_exp_f32_e32 v204, v140
	v_add_f32_e32 v128, v200, v128
	v_exp_f32_e32 v205, v141
	v_add_f32_e32 v128, v201, v128
	v_exp_f32_e32 v206, v142
	v_add_f32_e32 v128, v202, v128
	v_exp_f32_e32 v192, v192
	v_add_f32_e32 v128, v203, v128
	v_add_f32_e32 v128, v204, v128
	v_add_f32_e32 v128, v205, v128
	v_add_f32_e32 v128, v206, v128
	v_add_f32_e32 v128, v192, v128
	v_mov_b32_e32 v129, v128
	s_nop 1
	v_permlane32_swap_b32_e32 v128, v129
	v_add_f32_e32 v144, v128, v129
	v_fmac_f32_e32 v144, v232, v233
	v_cvt_pk_bf16_f32 v128, v143, v145
	v_cvt_pk_bf16_f32 v129, v146, v147
	v_cvt_pk_bf16_f32 v130, v148, v149
	v_cvt_pk_bf16_f32 v131, v150, v151
	v_cvt_pk_bf16_f32 v136, v152, v153
	v_cvt_pk_bf16_f32 v137, v154, v155
	v_cvt_pk_bf16_f32 v138, v156, v157
	v_cvt_pk_bf16_f32 v139, v158, v159
	v_cvt_pk_bf16_f32 v132, v193, v194
	v_cvt_pk_bf16_f32 v133, v195, v196
	v_cvt_pk_bf16_f32 v134, v197, v198
	v_cvt_pk_bf16_f32 v135, v199, v135
	v_cvt_pk_bf16_f32 v140, v200, v201
	v_cvt_pk_bf16_f32 v141, v202, v203
	v_cvt_pk_bf16_f32 v142, v204, v205
	v_cvt_pk_bf16_f32 v143, v206, v192
	v_lshl_add_u32 v145, s76, 15, v230
	ds_read_b64_tr_b16 v[146:147], v145 offset:0
	ds_read_b64_tr_b16 v[148:149], v145 offset:4096
	ds_read_b64_tr_b16 v[150:151], v145 offset:8192
	ds_read_b64_tr_b16 v[152:153], v145 offset:12288
	ds_read_b64_tr_b16 v[154:155], v145 offset:16384
	ds_read_b64_tr_b16 v[156:157], v145 offset:20480
	ds_read_b64_tr_b16 v[192:193], v145 offset:24576
	ds_read_b64_tr_b16 v[194:195], v145 offset:28672
	ds_read_b64_tr_b16 v[196:197], v145 offset:512
	ds_read_b64_tr_b16 v[198:199], v145 offset:4608
	ds_read_b64_tr_b16 v[200:201], v145 offset:8704
	ds_read_b64_tr_b16 v[202:203], v145 offset:12800
	ds_read_b64_tr_b16 v[204:205], v145 offset:16896
	ds_read_b64_tr_b16 v[206:207], v145 offset:20992
	s_waitcnt lgkmcnt(12)
	s_nop 0
	v_mfma_f32_32x32x16_bf16 v[0:15], v[128:131], v[146:149], v[0:15]
	ds_read_b64_tr_b16 v[232:233], v145 offset:25088
	ds_read_b64_tr_b16 v[234:235], v145 offset:29184
	s_waitcnt lgkmcnt(12)
	v_mfma_f32_32x32x16_bf16 v[0:15], v[136:139], v[150:153], v[0:15]
	ds_read_b64_tr_b16 v[146:147], v145 offset:1024
	ds_read_b64_tr_b16 v[148:149], v145 offset:5120
	s_waitcnt lgkmcnt(12)
	v_mfma_f32_32x32x16_bf16 v[0:15], v[132:135], v[154:157], v[0:15]
	ds_read_b64_tr_b16 v[150:151], v145 offset:9216
	ds_read_b64_tr_b16 v[152:153], v145 offset:13312
	s_waitcnt lgkmcnt(12)
	v_mfma_f32_32x32x16_bf16 v[0:15], v[140:143], v[192:195], v[0:15]
	ds_read_b64_tr_b16 v[154:155], v145 offset:17408
	ds_read_b64_tr_b16 v[156:157], v145 offset:21504
	s_waitcnt lgkmcnt(12)
	v_mfma_f32_32x32x16_bf16 v[112:127], v[128:131], v[196:199], v[112:127]
	ds_read_b64_tr_b16 v[192:193], v145 offset:25600
	ds_read_b64_tr_b16 v[194:195], v145 offset:29696
	s_waitcnt lgkmcnt(12)
	v_mfma_f32_32x32x16_bf16 v[112:127], v[136:139], v[200:203], v[112:127]
	ds_read_b64_tr_b16 v[196:197], v145 offset:1536
	ds_read_b64_tr_b16 v[198:199], v145 offset:5632
	s_waitcnt lgkmcnt(12)
	v_mfma_f32_32x32x16_bf16 v[112:127], v[132:135], v[204:207], v[112:127]
	ds_read_b64_tr_b16 v[200:201], v145 offset:9728
	ds_read_b64_tr_b16 v[202:203], v145 offset:13824
	s_waitcnt lgkmcnt(12)
	v_mfma_f32_32x32x16_bf16 v[112:127], v[140:143], v[232:235], v[112:127]
	ds_read_b64_tr_b16 v[204:205], v145 offset:17920
	ds_read_b64_tr_b16 v[206:207], v145 offset:22016
	s_waitcnt lgkmcnt(12)
	v_mfma_f32_32x32x16_bf16 v[96:111], v[128:131], v[146:149], v[96:111]
	ds_read_b64_tr_b16 v[232:233], v145 offset:26112
	ds_read_b64_tr_b16 v[234:235], v145 offset:30208
	s_waitcnt lgkmcnt(12)
	v_mfma_f32_32x32x16_bf16 v[96:111], v[136:139], v[150:153], v[96:111]
	ds_read_b64_tr_b16 v[146:147], v145 offset:2048
	ds_read_b64_tr_b16 v[148:149], v145 offset:6144
	s_waitcnt lgkmcnt(12)
	v_mfma_f32_32x32x16_bf16 v[96:111], v[132:135], v[154:157], v[96:111]
	ds_read_b64_tr_b16 v[150:151], v145 offset:10240
	ds_read_b64_tr_b16 v[152:153], v145 offset:14336
	s_waitcnt lgkmcnt(12)
	v_mfma_f32_32x32x16_bf16 v[96:111], v[140:143], v[192:195], v[96:111]
	ds_read_b64_tr_b16 v[154:155], v145 offset:18432
	ds_read_b64_tr_b16 v[156:157], v145 offset:22528
	s_waitcnt lgkmcnt(12)
	v_mfma_f32_32x32x16_bf16 v[80:95], v[128:131], v[196:199], v[80:95]
	ds_read_b64_tr_b16 v[192:193], v145 offset:26624
	ds_read_b64_tr_b16 v[194:195], v145 offset:30720
	s_waitcnt lgkmcnt(12)
	v_mfma_f32_32x32x16_bf16 v[80:95], v[136:139], v[200:203], v[80:95]
	ds_read_b64_tr_b16 v[196:197], v145 offset:2560
	ds_read_b64_tr_b16 v[198:199], v145 offset:6656
	s_waitcnt lgkmcnt(12)
	v_mfma_f32_32x32x16_bf16 v[80:95], v[132:135], v[204:207], v[80:95]
	ds_read_b64_tr_b16 v[200:201], v145 offset:10752
	ds_read_b64_tr_b16 v[202:203], v145 offset:14848
	s_waitcnt lgkmcnt(12)
	v_mfma_f32_32x32x16_bf16 v[80:95], v[140:143], v[232:235], v[80:95]
	ds_read_b64_tr_b16 v[204:205], v145 offset:18944
	ds_read_b64_tr_b16 v[206:207], v145 offset:23040
	s_waitcnt lgkmcnt(12)
	v_mfma_f32_32x32x16_bf16 v[64:79], v[128:131], v[146:149], v[64:79]
	ds_read_b64_tr_b16 v[232:233], v145 offset:27136
	ds_read_b64_tr_b16 v[234:235], v145 offset:31232
	s_waitcnt lgkmcnt(12)
	v_mfma_f32_32x32x16_bf16 v[64:79], v[136:139], v[150:153], v[64:79]
	ds_read_b64_tr_b16 v[146:147], v145 offset:3072
	ds_read_b64_tr_b16 v[148:149], v145 offset:7168
	s_waitcnt lgkmcnt(12)
	v_mfma_f32_32x32x16_bf16 v[64:79], v[132:135], v[154:157], v[64:79]
	ds_read_b64_tr_b16 v[150:151], v145 offset:11264
	ds_read_b64_tr_b16 v[152:153], v145 offset:15360
	s_waitcnt lgkmcnt(12)
	v_mfma_f32_32x32x16_bf16 v[64:79], v[140:143], v[192:195], v[64:79]
	ds_read_b64_tr_b16 v[154:155], v145 offset:19456
	ds_read_b64_tr_b16 v[156:157], v145 offset:23552
	s_waitcnt lgkmcnt(12)
	v_mfma_f32_32x32x16_bf16 v[48:63], v[128:131], v[196:199], v[48:63]
	ds_read_b64_tr_b16 v[192:193], v145 offset:27648
	ds_read_b64_tr_b16 v[194:195], v145 offset:31744
	s_waitcnt lgkmcnt(12)
	v_mfma_f32_32x32x16_bf16 v[48:63], v[136:139], v[200:203], v[48:63]
	ds_read_b64_tr_b16 v[196:197], v145 offset:3584
	ds_read_b64_tr_b16 v[198:199], v145 offset:7680
	s_waitcnt lgkmcnt(12)
	v_mfma_f32_32x32x16_bf16 v[48:63], v[132:135], v[204:207], v[48:63]
	ds_read_b64_tr_b16 v[200:201], v145 offset:11776
	ds_read_b64_tr_b16 v[202:203], v145 offset:15872
	s_waitcnt lgkmcnt(12)
	v_mfma_f32_32x32x16_bf16 v[48:63], v[140:143], v[232:235], v[48:63]
	ds_read_b64_tr_b16 v[204:205], v145 offset:19968
	ds_read_b64_tr_b16 v[206:207], v145 offset:24064
	s_waitcnt lgkmcnt(12)
	v_mfma_f32_32x32x16_bf16 v[32:47], v[128:131], v[146:149], v[32:47]
	ds_read_b64_tr_b16 v[232:233], v145 offset:28160
	ds_read_b64_tr_b16 v[234:235], v145 offset:32256
	s_waitcnt lgkmcnt(12)
	v_mfma_f32_32x32x16_bf16 v[32:47], v[136:139], v[150:153], v[32:47]
	s_waitcnt lgkmcnt(10)
	v_mfma_f32_32x32x16_bf16 v[32:47], v[132:135], v[154:157], v[32:47]
	s_waitcnt lgkmcnt(8)
	v_mfma_f32_32x32x16_bf16 v[32:47], v[140:143], v[192:195], v[32:47]
	s_waitcnt lgkmcnt(6)
	v_mfma_f32_32x32x16_bf16 v[16:31], v[128:131], v[196:199], v[16:31]
	s_add_i32 s4, s76, 1
	s_cmp_lg_u32 s76, 2
	s_cselect_b32 s76, s4, 0
	s_add_i32 s4, s74, 1
	s_cmp_lg_u32 s74, 2
	s_cselect_b32 s74, s4, 0
	s_add_u32 s22, s22, 0x20000
	s_waitcnt lgkmcnt(4)
	v_mfma_f32_32x32x16_bf16 v[16:31], v[136:139], v[200:203], v[16:31]
	s_addc_u32 s23, s23, 0
	s_add_i32 s86, s86, 1
	s_cmp_eq_u32 s22, 0x800000
	s_waitcnt lgkmcnt(2)
	v_mfma_f32_32x32x16_bf16 v[16:31], v[132:135], v[204:207], v[16:31]
	s_waitcnt lgkmcnt(0)
	v_mfma_f32_32x32x16_bf16 v[16:31], v[140:143], v[232:235], v[16:31]
	s_cbranch_scc1 .LBB0_521
	v_mov_b32_e32 v232, v144
	s_cmp_eq_u32 s22, 0x7e0000
	s_mov_b64 s[4:5], -1
	s_cbranch_scc1 .LBB0_510

.LBB0_910:
	v_cndmask_b32_e64 v231, v234, v231, s[4:5]
	v_mul_f32_e32 v192, 0xbe0293ee, v231
	v_fmamk_f32 v144, v144, 0x3e0293ee, v192
	v_fmamk_f32 v145, v145, 0x3e0293ee, v192
	v_fmamk_f32 v146, v146, 0x3e0293ee, v192
	v_fmamk_f32 v147, v147, 0x3e0293ee, v192
	v_fmamk_f32 v148, v148, 0x3e0293ee, v192
	v_fmamk_f32 v149, v149, 0x3e0293ee, v192
	v_fmamk_f32 v150, v150, 0x3e0293ee, v192
	v_fmamk_f32 v151, v151, 0x3e0293ee, v192
	v_fmamk_f32 v152, v152, 0x3e0293ee, v192
	v_fmamk_f32 v153, v153, 0x3e0293ee, v192
	v_fmamk_f32 v154, v154, 0x3e0293ee, v192
	v_fmamk_f32 v155, v155, 0x3e0293ee, v192
	v_fmamk_f32 v156, v156, 0x3e0293ee, v192
	v_fmamk_f32 v157, v157, 0x3e0293ee, v192
	v_fmamk_f32 v158, v158, 0x3e0293ee, v192
	v_fmamk_f32 v159, v159, 0x3e0293ee, v192
	v_fmamk_f32 v128, v128, 0x3e0293ee, v192
	v_fmamk_f32 v129, v129, 0x3e0293ee, v192
	v_fmamk_f32 v130, v130, 0x3e0293ee, v192
	v_fmamk_f32 v131, v131, 0x3e0293ee, v192
	v_fmamk_f32 v132, v132, 0x3e0293ee, v192
	v_fmamk_f32 v133, v133, 0x3e0293ee, v192
	v_fmamk_f32 v134, v134, 0x3e0293ee, v192
	v_fmamk_f32 v135, v135, 0x3e0293ee, v192
	v_fmamk_f32 v136, v136, 0x3e0293ee, v192
	v_fmamk_f32 v137, v137, 0x3e0293ee, v192
	v_fmamk_f32 v138, v138, 0x3e0293ee, v192
	v_fmamk_f32 v139, v139, 0x3e0293ee, v192
	v_fmamk_f32 v140, v140, 0x3e0293ee, v192
	v_fmamk_f32 v141, v141, 0x3e0293ee, v192
	v_fmamk_f32 v142, v142, 0x3e0293ee, v192
	v_fmac_f32_e32 v192, 0x3e0293ee, v143
	v_exp_f32_e32 v143, v144
	v_exp_f32_e32 v145, v145
	v_exp_f32_e32 v146, v146
	v_exp_f32_e32 v147, v147
	v_exp_f32_e32 v148, v148
	v_exp_f32_e32 v193, v128
	v_exp_f32_e32 v149, v149
	v_add_f32_e32 v128, v145, v143
	v_exp_f32_e32 v150, v150
	v_add_f32_e32 v128, v146, v128
	v_exp_f32_e32 v151, v151
	v_add_f32_e32 v128, v147, v128
	v_exp_f32_e32 v152, v152
	v_add_f32_e32 v128, v148, v128
	v_exp_f32_e32 v153, v153
	v_add_f32_e32 v128, v149, v128
	v_exp_f32_e32 v154, v154
	v_add_f32_e32 v128, v150, v128
	v_exp_f32_e32 v155, v155
	v_add_f32_e32 v128, v151, v128
	v_exp_f32_e32 v156, v156
	v_add_f32_e32 v128, v152, v128
	v_exp_f32_e32 v157, v157
	v_add_f32_e32 v128, v153, v128
	v_exp_f32_e32 v158, v158
	v_add_f32_e32 v128, v154, v128
	v_exp_f32_e32 v159, v159
	v_add_f32_e32 v128, v155, v128
	v_add_f32_e32 v128, v156, v128
	v_exp_f32_e32 v194, v129
	v_add_f32_e32 v128, v157, v128
	v_exp_f32_e32 v195, v130
	v_add_f32_e32 v128, v158, v128
	v_exp_f32_e32 v196, v131
	v_add_f32_e32 v128, v159, v128
	v_exp_f32_e32 v197, v132
	v_add_f32_e32 v128, v193, v128
	v_exp_f32_e32 v198, v133
	v_add_f32_e32 v128, v194, v128
	v_exp_f32_e32 v199, v134
	v_add_f32_e32 v128, v195, v128
	v_exp_f32_e32 v135, v135
	v_add_f32_e32 v128, v196, v128
	v_exp_f32_e32 v200, v136
	v_add_f32_e32 v128, v197, v128
	v_exp_f32_e32 v201, v137
	v_add_f32_e32 v128, v198, v128
	v_exp_f32_e32 v202, v138
	v_add_f32_e32 v128, v199, v128
	v_exp_f32_e32 v203, v139
	v_add_f32_e32 v128, v135, v128
	v_exp_f32_e32 v204, v140
	v_add_f32_e32 v128, v200, v128
	v_exp_f32_e32 v205, v141
	v_add_f32_e32 v128, v201, v128
	v_exp_f32_e32 v206, v142
	v_add_f32_e32 v128, v202, v128
	v_exp_f32_e32 v192, v192
	v_add_f32_e32 v128, v203, v128
	v_add_f32_e32 v128, v204, v128
	v_add_f32_e32 v128, v205, v128
	v_add_f32_e32 v128, v206, v128
	v_add_f32_e32 v128, v192, v128
	v_mov_b32_e32 v129, v128
	s_nop 1
	v_permlane32_swap_b32_e32 v128, v129
	v_add_f32_e32 v144, v128, v129
	v_fmac_f32_e32 v144, v232, v233
	v_cvt_pk_bf16_f32 v128, v143, v145
	v_cvt_pk_bf16_f32 v129, v146, v147
	v_cvt_pk_bf16_f32 v130, v148, v149
	v_cvt_pk_bf16_f32 v131, v150, v151
	v_cvt_pk_bf16_f32 v136, v152, v153
	v_cvt_pk_bf16_f32 v137, v154, v155
	v_cvt_pk_bf16_f32 v138, v156, v157
	v_cvt_pk_bf16_f32 v139, v158, v159
	v_cvt_pk_bf16_f32 v132, v193, v194
	v_cvt_pk_bf16_f32 v133, v195, v196
	v_cvt_pk_bf16_f32 v134, v197, v198
	v_cvt_pk_bf16_f32 v135, v199, v135
	v_cvt_pk_bf16_f32 v140, v200, v201
	v_cvt_pk_bf16_f32 v141, v202, v203
	v_cvt_pk_bf16_f32 v142, v204, v205
	v_cvt_pk_bf16_f32 v143, v206, v192
	v_lshl_add_u32 v145, s80, 15, v230
	ds_read_b64_tr_b16 v[146:147], v145 offset:0
	ds_read_b64_tr_b16 v[148:149], v145 offset:4096
	ds_read_b64_tr_b16 v[150:151], v145 offset:8192
	ds_read_b64_tr_b16 v[152:153], v145 offset:12288
	ds_read_b64_tr_b16 v[154:155], v145 offset:16384
	ds_read_b64_tr_b16 v[156:157], v145 offset:20480
	ds_read_b64_tr_b16 v[192:193], v145 offset:24576
	ds_read_b64_tr_b16 v[194:195], v145 offset:28672
	ds_read_b64_tr_b16 v[196:197], v145 offset:512
	ds_read_b64_tr_b16 v[198:199], v145 offset:4608
	ds_read_b64_tr_b16 v[200:201], v145 offset:8704
	ds_read_b64_tr_b16 v[202:203], v145 offset:12800
	ds_read_b64_tr_b16 v[204:205], v145 offset:16896
	ds_read_b64_tr_b16 v[206:207], v145 offset:20992
	s_waitcnt lgkmcnt(12)
	s_nop 0
	v_mfma_f32_32x32x16_bf16 v[0:15], v[128:131], v[146:149], v[0:15]
	ds_read_b64_tr_b16 v[232:233], v145 offset:25088
	ds_read_b64_tr_b16 v[234:235], v145 offset:29184
	s_waitcnt lgkmcnt(12)
	v_mfma_f32_32x32x16_bf16 v[0:15], v[136:139], v[150:153], v[0:15]
	ds_read_b64_tr_b16 v[146:147], v145 offset:1024
	ds_read_b64_tr_b16 v[148:149], v145 offset:5120
	s_waitcnt lgkmcnt(12)
	v_mfma_f32_32x32x16_bf16 v[0:15], v[132:135], v[154:157], v[0:15]
	ds_read_b64_tr_b16 v[150:151], v145 offset:9216
	ds_read_b64_tr_b16 v[152:153], v145 offset:13312
	s_waitcnt lgkmcnt(12)
	v_mfma_f32_32x32x16_bf16 v[0:15], v[140:143], v[192:195], v[0:15]
	ds_read_b64_tr_b16 v[154:155], v145 offset:17408
	ds_read_b64_tr_b16 v[156:157], v145 offset:21504
	s_waitcnt lgkmcnt(12)
	v_mfma_f32_32x32x16_bf16 v[112:127], v[128:131], v[196:199], v[112:127]
	ds_read_b64_tr_b16 v[192:193], v145 offset:25600
	ds_read_b64_tr_b16 v[194:195], v145 offset:29696
	s_waitcnt lgkmcnt(12)
	v_mfma_f32_32x32x16_bf16 v[112:127], v[136:139], v[200:203], v[112:127]
	ds_read_b64_tr_b16 v[196:197], v145 offset:1536
	ds_read_b64_tr_b16 v[198:199], v145 offset:5632
	s_waitcnt lgkmcnt(12)
	v_mfma_f32_32x32x16_bf16 v[112:127], v[132:135], v[204:207], v[112:127]
	ds_read_b64_tr_b16 v[200:201], v145 offset:9728
	ds_read_b64_tr_b16 v[202:203], v145 offset:13824
	s_waitcnt lgkmcnt(12)
	v_mfma_f32_32x32x16_bf16 v[112:127], v[140:143], v[232:235], v[112:127]
	ds_read_b64_tr_b16 v[204:205], v145 offset:17920
	ds_read_b64_tr_b16 v[206:207], v145 offset:22016
	s_waitcnt lgkmcnt(12)
	v_mfma_f32_32x32x16_bf16 v[96:111], v[128:131], v[146:149], v[96:111]
	ds_read_b64_tr_b16 v[232:233], v145 offset:26112
	ds_read_b64_tr_b16 v[234:235], v145 offset:30208
	s_waitcnt lgkmcnt(12)
	v_mfma_f32_32x32x16_bf16 v[96:111], v[136:139], v[150:153], v[96:111]
	ds_read_b64_tr_b16 v[146:147], v145 offset:2048
	ds_read_b64_tr_b16 v[148:149], v145 offset:6144
	s_waitcnt lgkmcnt(12)
	v_mfma_f32_32x32x16_bf16 v[96:111], v[132:135], v[154:157], v[96:111]
	ds_read_b64_tr_b16 v[150:151], v145 offset:10240
	ds_read_b64_tr_b16 v[152:153], v145 offset:14336
	s_waitcnt lgkmcnt(12)
	v_mfma_f32_32x32x16_bf16 v[96:111], v[140:143], v[192:195], v[96:111]
	ds_read_b64_tr_b16 v[154:155], v145 offset:18432
	ds_read_b64_tr_b16 v[156:157], v145 offset:22528
	s_waitcnt lgkmcnt(12)
	v_mfma_f32_32x32x16_bf16 v[80:95], v[128:131], v[196:199], v[80:95]
	ds_read_b64_tr_b16 v[192:193], v145 offset:26624
	ds_read_b64_tr_b16 v[194:195], v145 offset:30720
	s_waitcnt lgkmcnt(12)
	v_mfma_f32_32x32x16_bf16 v[80:95], v[136:139], v[200:203], v[80:95]
	ds_read_b64_tr_b16 v[196:197], v145 offset:2560
	ds_read_b64_tr_b16 v[198:199], v145 offset:6656
	s_waitcnt lgkmcnt(12)
	v_mfma_f32_32x32x16_bf16 v[80:95], v[132:135], v[204:207], v[80:95]
	ds_read_b64_tr_b16 v[200:201], v145 offset:10752
	ds_read_b64_tr_b16 v[202:203], v145 offset:14848
	s_waitcnt lgkmcnt(12)
	v_mfma_f32_32x32x16_bf16 v[80:95], v[140:143], v[232:235], v[80:95]
	ds_read_b64_tr_b16 v[204:205], v145 offset:18944
	ds_read_b64_tr_b16 v[206:207], v145 offset:23040
	s_waitcnt lgkmcnt(12)
	v_mfma_f32_32x32x16_bf16 v[64:79], v[128:131], v[146:149], v[64:79]
	ds_read_b64_tr_b16 v[232:233], v145 offset:27136
	ds_read_b64_tr_b16 v[234:235], v145 offset:31232
	s_waitcnt lgkmcnt(12)
	v_mfma_f32_32x32x16_bf16 v[64:79], v[136:139], v[150:153], v[64:79]
	ds_read_b64_tr_b16 v[146:147], v145 offset:3072
	ds_read_b64_tr_b16 v[148:149], v145 offset:7168
	s_waitcnt lgkmcnt(12)
	v_mfma_f32_32x32x16_bf16 v[64:79], v[132:135], v[154:157], v[64:79]
	ds_read_b64_tr_b16 v[150:151], v145 offset:11264
	ds_read_b64_tr_b16 v[152:153], v145 offset:15360
	s_waitcnt lgkmcnt(12)
	v_mfma_f32_32x32x16_bf16 v[64:79], v[140:143], v[192:195], v[64:79]
	ds_read_b64_tr_b16 v[154:155], v145 offset:19456
	ds_read_b64_tr_b16 v[156:157], v145 offset:23552
	s_waitcnt lgkmcnt(12)
	v_mfma_f32_32x32x16_bf16 v[48:63], v[128:131], v[196:199], v[48:63]
	ds_read_b64_tr_b16 v[192:193], v145 offset:27648
	ds_read_b64_tr_b16 v[194:195], v145 offset:31744
	s_waitcnt lgkmcnt(12)
	v_mfma_f32_32x32x16_bf16 v[48:63], v[136:139], v[200:203], v[48:63]
	ds_read_b64_tr_b16 v[196:197], v145 offset:3584
	ds_read_b64_tr_b16 v[198:199], v145 offset:7680
	s_waitcnt lgkmcnt(12)
	v_mfma_f32_32x32x16_bf16 v[48:63], v[132:135], v[204:207], v[48:63]
	ds_read_b64_tr_b16 v[200:201], v145 offset:11776
	ds_read_b64_tr_b16 v[202:203], v145 offset:15872
	s_waitcnt lgkmcnt(12)
	v_mfma_f32_32x32x16_bf16 v[48:63], v[140:143], v[232:235], v[48:63]
	ds_read_b64_tr_b16 v[204:205], v145 offset:19968
	ds_read_b64_tr_b16 v[206:207], v145 offset:24064
	s_waitcnt lgkmcnt(12)
	v_mfma_f32_32x32x16_bf16 v[32:47], v[128:131], v[146:149], v[32:47]
	ds_read_b64_tr_b16 v[232:233], v145 offset:28160
	ds_read_b64_tr_b16 v[234:235], v145 offset:32256
	s_waitcnt lgkmcnt(12)
	v_mfma_f32_32x32x16_bf16 v[32:47], v[136:139], v[150:153], v[32:47]
	s_waitcnt lgkmcnt(10)
	v_mfma_f32_32x32x16_bf16 v[32:47], v[132:135], v[154:157], v[32:47]
	s_waitcnt lgkmcnt(8)
	v_mfma_f32_32x32x16_bf16 v[32:47], v[140:143], v[192:195], v[32:47]
	s_waitcnt lgkmcnt(6)
	v_mfma_f32_32x32x16_bf16 v[16:31], v[128:131], v[196:199], v[16:31]
	s_add_i32 s4, s80, 1
	s_cmp_lg_u32 s80, 2
	s_cselect_b32 s80, s4, 0
	s_add_i32 s4, s78, 1
	s_cmp_lg_u32 s78, 2
	s_cselect_b32 s78, s4, 0
	s_add_u32 s22, s22, 0x20000
	s_waitcnt lgkmcnt(4)
	v_mfma_f32_32x32x16_bf16 v[16:31], v[136:139], v[200:203], v[16:31]
	s_addc_u32 s23, s23, 0
	s_add_i32 s86, s86, 1
	s_cmp_eq_u32 s22, 0x800000
	s_waitcnt lgkmcnt(2)
	v_mfma_f32_32x32x16_bf16 v[16:31], v[132:135], v[204:207], v[16:31]
	s_waitcnt lgkmcnt(0)
	v_mfma_f32_32x32x16_bf16 v[16:31], v[140:143], v[232:235], v[16:31]
	s_cbranch_scc1 .LBB0_914
	v_mov_b32_e32 v232, v144
	s_cmp_eq_u32 s22, 0x7e0000
	s_mov_b64 s[4:5], -1
	s_cbranch_scc1 .LBB0_903
